# speedup vs baseline: 1.0048x; 1.0019x over previous
; __device__ __forceinline__ u32x2 pack4(f32x4 v) { u32x2 o = {cvtpk(v[0], v[1]), cvtpk(v[2], v[3])}; return o; }
; static __device__ __forceinline__ void phase_g1b(const Params& p, u16* sm) {
;     ...
; #pragma unroll
;     for (int mt = 0; mt < 4; ++mt)
; #pragma unroll
;       for (int nt = 0; nt < 4; ++nt) {
;         const int m = m0 + wr * 64 + mt * 16 + l15, n = n0 + wc * 64 + nt * 16 + quad * 4;
;         *(u32x2*)(Gp + (size_t)m * 2048 + n) = pack4(acc[mt][nt]);
;       }
.LBB0_428:
	v_lshl_add_u32 v66, s84, 7, v80
	v_ashrrev_i32_e32 v67, 31, v66
	v_or_b32_e32 v64, s85, v81
	v_lshlrev_b64 v[68:69], 12, v[66:67]
	v_lshl_add_u64 v[68:69], s[18:19], 0, v[68:69]
	v_lshlrev_b32_e32 v64, 1, v64
	v_cvt_pk_bf16_f32 v60, v60, v61
	v_cvt_pk_bf16_f32 v61, v62, v63
	v_cvt_pk_bf16_f32 v62, v56, v57
	v_cvt_pk_bf16_f32 v63, v58, v59
	v_cvt_pk_bf16_f32 v52, v52, v53
	v_cvt_pk_bf16_f32 v53, v54, v55
	v_cvt_pk_bf16_f32 v54, v48, v49
	v_cvt_pk_bf16_f32 v55, v50, v51
	v_and_b32_e32 v56, 4, v81
	v_lshlrev_b32_e32 v57, 2, v56
	v_lshl_add_u32 v57, v56, 1, v57
	v_add_u32_e32 v64, v64, v57
	v_lshl_add_u64 v[56:57], v[68:69], 0, v[64:65]
	v_or_b32_e32 v48, 16, v66
	v_ashrrev_i32_e32 v49, 31, v48
	v_lshlrev_b64 v[48:49], 12, v[48:49]
	v_lshl_add_u64 v[48:49], s[18:19], 0, v[48:49]
	v_lshl_add_u64 v[48:49], v[48:49], 0, v[64:65]
	v_or_b32_e32 v50, 32, v66
	v_ashrrev_i32_e32 v51, 31, v50
	v_lshlrev_b64 v[50:51], 12, v[50:51]
	v_lshl_add_u64 v[50:51], s[18:19], 0, v[50:51]
	v_lshl_add_u64 v[50:51], v[50:51], 0, v[64:65]
	v_or_b32_e32 v58, 48, v66
	v_ashrrev_i32_e32 v59, 31, v58
	v_lshlrev_b64 v[58:59], 12, v[58:59]
	v_lshl_add_u64 v[58:59], s[18:19], 0, v[58:59]
	v_lshl_add_u64 v[58:59], v[58:59], 0, v[64:65]
	v_cvt_pk_bf16_f32 v44, v44, v45
	v_cvt_pk_bf16_f32 v45, v46, v47
	v_cvt_pk_bf16_f32 v46, v40, v41
	v_cvt_pk_bf16_f32 v47, v42, v43
	v_cvt_pk_bf16_f32 v36, v36, v37
	v_cvt_pk_bf16_f32 v37, v38, v39
	v_cvt_pk_bf16_f32 v38, v32, v33
	v_cvt_pk_bf16_f32 v39, v34, v35
	v_cvt_pk_bf16_f32 v28, v28, v29
	v_cvt_pk_bf16_f32 v29, v30, v31
	v_cvt_pk_bf16_f32 v30, v24, v25
	v_cvt_pk_bf16_f32 v31, v26, v27
	v_cvt_pk_bf16_f32 v20, v20, v21
	v_cvt_pk_bf16_f32 v21, v22, v23
	v_cvt_pk_bf16_f32 v22, v16, v17
	v_cvt_pk_bf16_f32 v23, v18, v19
	v_cvt_pk_bf16_f32 v12, v12, v13
	v_cvt_pk_bf16_f32 v13, v14, v15
	v_cvt_pk_bf16_f32 v14, v8, v9
	v_cvt_pk_bf16_f32 v15, v10, v11
	v_cvt_pk_bf16_f32 v4, v4, v5
	v_cvt_pk_bf16_f32 v5, v6, v7
	v_cvt_pk_bf16_f32 v6, v0, v1
	v_cvt_pk_bf16_f32 v7, v2, v3
	s_mov_b64 s[20:21], -1
	s_andn2_b64 vcc, exec, s[48:49]
	s_mov_b32 s12, s83
	s_mov_b32 s13, s82
	v_permlane16_swap_b32_e32 v60, v62
	v_permlane16_swap_b32_e32 v61, v63
	v_permlane16_swap_b32_e32 v52, v54
	v_permlane16_swap_b32_e32 v53, v55
	v_permlane16_swap_b32_e32 v44, v46
	v_permlane16_swap_b32_e32 v45, v47
	v_permlane16_swap_b32_e32 v36, v38
	v_permlane16_swap_b32_e32 v37, v39
	v_permlane16_swap_b32_e32 v28, v30
	v_permlane16_swap_b32_e32 v29, v31
	v_permlane16_swap_b32_e32 v20, v22
	v_permlane16_swap_b32_e32 v21, v23
	v_permlane16_swap_b32_e32 v12, v14
	v_permlane16_swap_b32_e32 v13, v15
	v_permlane16_swap_b32_e32 v4, v6
	v_permlane16_swap_b32_e32 v5, v7
	global_store_dwordx4 v[56:57], v[60:63], off
	global_store_dwordx4 v[56:57], v[52:55], off offset:64
	global_store_dwordx4 v[48:49], v[44:47], off
	global_store_dwordx4 v[48:49], v[36:39], off offset:64
	global_store_dwordx4 v[50:51], v[28:31], off
	global_store_dwordx4 v[50:51], v[20:23], off offset:64
	global_store_dwordx4 v[58:59], v[12:15], off
	global_store_dwordx4 v[58:59], v[4:7], off offset:64
	s_cbranch_vccz .LBB0_446
